# post-P0 grid barrier: cooperative-groups flat barrier replaced by a pass through the XCD-hierarchical barrier instance (one L2 write-back per XCD instead of per workgroup)
# baseline (speedup 1.0000x reference)
.LBB0_68:
.LBB0_78:
	v_readlane_b32 s6, v253, 0
	v_readlane_b32 s7, v253, 1
	s_add_u32 s4, s6, 0x4200
	s_addc_u32 s5, s7, 0
	v_writelane_b32 v253, s4, 5
	s_mov_b64 s[78:79], src_shared_base
	s_mul_i32 s34, s74, 0x38000
	v_writelane_b32 v253, s5, 6
	s_add_u32 s4, s6, 0x4400
	s_addc_u32 s5, s7, 0
	v_writelane_b32 v253, s4, 7
	s_mov_b32 s47, 0
	s_mov_b32 s88, 0xfff90000
	v_writelane_b32 v253, s5, 8
	s_add_u32 s4, s6, 0x4500
	s_addc_u32 s5, s7, 0
	v_writelane_b32 v253, s4, 9
	v_mov_b32_e32 v198, 0x358637bd
	v_mov_b32_e32 v199, 1
	v_writelane_b32 v253, s5, 10
	s_add_u32 s4, s6, 0x4600
	s_addc_u32 s5, s7, 0
	v_writelane_b32 v253, s4, 11
	v_mov_b64_e32 v[182:183], 0x738
	v_mov_b64_e32 v[184:185], 0x737
	v_writelane_b32 v253, s5, 12
	s_add_u32 s4, s6, 0x4700
	s_addc_u32 s5, s7, 0
	v_writelane_b32 v253, s4, 13
	v_mov_b32_e32 v200, 0x42800000
	v_not_b32_e32 v201, 63
	v_writelane_b32 v253, s5, 14
	s_add_u32 s4, s6, 0x4800
	s_addc_u32 s5, s7, 0
	v_writelane_b32 v253, s4, 15
	v_mov_b32_e32 v202, 0x6c00
	v_mov_b32_e32 v203, 0xc000
	v_writelane_b32 v253, s5, 16
	s_add_u32 s4, s6, 0x4900
	s_addc_u32 s5, s7, 0
	v_writelane_b32 v253, s4, 17
	v_mov_b32_e32 v204, 0xc600
	v_mov_b32_e32 v205, 0xcc00
	v_writelane_b32 v253, s5, 18
	s_add_u32 s4, s6, 0x4a00
	s_addc_u32 s5, s7, 0
	v_writelane_b32 v253, s4, 19
	v_mov_b32_e32 v206, 0x12000
	v_mov_b32_e32 v207, 0x12600
	v_writelane_b32 v253, s5, 20
	s_add_u32 s4, s6, 0x4b00
	s_addc_u32 s5, s7, 0
	v_writelane_b32 v253, s4, 21
	v_mov_b32_e32 v208, 0x12c00
	v_mov_b32_e32 v209, 0xc00
	v_writelane_b32 v253, s5, 22
	s_add_u32 s4, s6, 0x4c00
	s_addc_u32 s5, s7, 0
	v_writelane_b32 v253, s4, 23
	v_mov_b32_e32 v210, 0x21000080
	s_movk_i32 s33, 0x1c00
	v_writelane_b32 v253, s5, 24
	s_add_u32 s4, s6, 0x4d00
	s_addc_u32 s5, s7, 0
	v_writelane_b32 v253, s4, 25
	s_movk_i32 s81, 0x1800
	s_movk_i32 s36, 0x6480
	v_writelane_b32 v253, s5, 26
	s_add_u32 s4, s6, 0x4e00
	s_addc_u32 s5, s7, 0
	v_writelane_b32 v253, s4, 27
	s_movk_i32 s84, 0x5ff
	s_mov_b32 s66, 0xbfb8aa3b
	v_writelane_b32 v253, s5, 28
	s_add_u32 s4, s6, 0x4f00
	s_addc_u32 s5, s7, 0
	v_writelane_b32 v253, s4, 29
	s_mov_b32 s82, 0x41000000
	s_mov_b64 s[16:17], 0x80
	v_writelane_b32 v253, s5, 30
	s_add_u32 s4, s6, 0x5000
	s_addc_u32 s5, s7, 0
	v_writelane_b32 v253, s4, 31
	s_mov_b64 s[86:87], 0x2400000
	s_mov_b32 s89, -1
	v_writelane_b32 v253, s5, 32
	s_add_u32 s4, s6, 0x5100
	s_addc_u32 s5, s7, 0
	v_writelane_b32 v253, s4, 33
	s_mov_b64 s[90:91], 0xe0000
	s_nop 0
	v_writelane_b32 v253, s5, 34
	s_add_u32 s4, s6, 0x5200
	s_addc_u32 s5, s7, 0
	v_writelane_b32 v253, s4, 35
	s_nop 1
	v_writelane_b32 v253, s5, 36
	s_add_u32 s4, s6, 0x5300
	s_addc_u32 s5, s7, 0
	v_writelane_b32 v253, s4, 37
	s_cmp_eq_u32 s30, 15
	s_nop 0
	v_writelane_b32 v253, s5, 38
	s_cselect_b64 s[4:5], -1, 0
	v_writelane_b32 v253, s4, 39
	s_cmp_eq_u32 s30, 14
	s_nop 0
	v_writelane_b32 v253, s5, 40
	s_cselect_b64 s[4:5], -1, 0
	v_writelane_b32 v253, s4, 41
	s_cmp_eq_u32 s30, 13
	s_nop 0
	v_writelane_b32 v253, s5, 42
	s_cselect_b64 s[4:5], -1, 0
	v_writelane_b32 v253, s4, 43
	s_cmp_eq_u32 s30, 12
	s_nop 0
	v_writelane_b32 v253, s5, 44
	s_cselect_b64 s[4:5], -1, 0
	v_writelane_b32 v253, s4, 45
	s_cmp_eq_u32 s30, 11
	s_nop 0
	v_writelane_b32 v253, s5, 46
	s_cselect_b64 s[4:5], -1, 0
	v_writelane_b32 v253, s4, 47
	s_cmp_eq_u32 s30, 10
	s_nop 0
	v_writelane_b32 v253, s5, 48
	s_cselect_b64 s[4:5], -1, 0
	v_writelane_b32 v253, s4, 49
	s_cmp_eq_u32 s30, 9
	s_nop 0
	v_writelane_b32 v253, s5, 50
	s_cselect_b64 s[4:5], -1, 0
	v_writelane_b32 v253, s4, 51
	s_cmp_eq_u32 s30, 8
	s_nop 0
	v_writelane_b32 v253, s5, 52
	s_cselect_b64 s[4:5], -1, 0
	v_writelane_b32 v253, s4, 53
	s_cmp_eq_u32 s30, 7
	s_nop 0
	v_writelane_b32 v253, s5, 54
	s_cselect_b64 s[4:5], -1, 0
	v_writelane_b32 v253, s4, 55
	s_cmp_eq_u32 s30, 6
	s_nop 0
	v_writelane_b32 v253, s5, 56
	s_cselect_b64 s[4:5], -1, 0
	v_writelane_b32 v253, s4, 57
	s_cmp_eq_u32 s30, 5
	s_nop 0
	v_writelane_b32 v253, s5, 58
	s_cselect_b64 s[4:5], -1, 0
	v_writelane_b32 v253, s4, 59
	s_cmp_eq_u32 s30, 4
	s_nop 0
	v_writelane_b32 v253, s5, 60
	s_cselect_b64 s[4:5], -1, 0
	v_writelane_b32 v253, s4, 61
	s_cmp_eq_u32 s30, 3
	s_nop 0
	v_writelane_b32 v253, s5, 62
	s_cselect_b64 s[4:5], -1, 0
	v_writelane_b32 v253, s4, 63
	s_cmp_eq_u32 s30, 2
	s_nop 0
	v_writelane_b32 v254, s5, 0
	s_cselect_b64 s[4:5], -1, 0
	v_writelane_b32 v254, s4, 1
	s_cmp_eq_u32 s30, 1
	s_nop 0
	v_writelane_b32 v254, s5, 2
	s_cselect_b64 s[4:5], -1, 0
	v_writelane_b32 v254, s4, 3
	s_cmp_eq_u32 s30, 0
	s_nop 0
	v_writelane_b32 v254, s5, 4
	s_cselect_b64 s[4:5], -1, 0
	v_writelane_b32 v254, s4, 5
	s_nop 1
	v_writelane_b32 v254, s5, 6
	s_lshl_b32 s4, s30, 8
	s_add_u32 s2, s2, s4
	s_addc_u32 s3, s3, 0
	s_add_u32 s4, s2, 0x1400
	s_addc_u32 s5, s3, 0
	v_writelane_b32 v254, s4, 7
	s_add_u32 s2, s2, 0x2400
	s_addc_u32 s3, s3, 0
	v_writelane_b32 v254, s5, 8
	v_writelane_b32 v254, s2, 9
	s_nop 1
	v_writelane_b32 v254, s3, 10
	s_add_u32 s2, s6, 0x7400
	s_addc_u32 s3, s7, 0
	v_writelane_b32 v254, s2, 11
	s_nop 1
	v_writelane_b32 v254, s3, 12
	s_add_u32 s2, s6, 0x7500
	s_addc_u32 s3, s7, 0
	v_writelane_b32 v254, s2, 13
	s_cmpk_lt_i32 s73, 0x738
	s_nop 0
	v_writelane_b32 v254, s3, 14
	s_cselect_b64 s[2:3], -1, 0
	v_writelane_b32 v254, s2, 15
	s_ashr_i32 s78, s73, 31
	s_ashr_i32 s80, s74, 31
	v_writelane_b32 v254, s3, 16
	s_lshr_b32 s2, s78, 29
	s_add_i32 s2, s73, s2
	s_and_b32 s3, s2, -8
	s_ashr_i32 s8, s2, 3
	s_sub_i32 s13, s73, s3
	s_lshl_b32 s30, s74, 5
	s_cmpk_lt_i32 s73, 0x80
	s_cselect_b64 s[4:5], -1, 0
	v_writelane_b32 v254, s4, 17
	s_ashr_i32 s6, s2, 5
	s_lshl_b32 s2, s13, 8
	v_writelane_b32 v254, s5, 18
	s_ashr_i32 s3, s2, 31
	v_writelane_b32 v254, s2, 19
	s_mul_hi_i32 s35, s30, 0x1c00
	s_nop 0
	v_writelane_b32 v254, s3, 20
	s_and_b32 s2, s8, 3
	v_writelane_b32 v254, s2, 21
	s_lshl_b32 s2, s73, 9
	v_writelane_b32 v254, s2, 22
	s_lshl_b32 s2, s74, 9
	v_writelane_b32 v254, s2, 23
	s_cmpk_lt_i32 s73, 0xb0
	s_mul_hi_i32 s2, s73, 0x2e8ba2e9
	s_cselect_b64 s[4:5], -1, 0
	s_lshr_b32 s3, s2, 31
	s_ashr_i32 s2, s2, 1
	s_add_i32 s2, s2, s3
	v_writelane_b32 v254, s4, 24
	s_mul_i32 s3, s2, 11
	s_sub_i32 s3, s73, s3
	v_writelane_b32 v254, s5, 25
	s_ashr_i32 s7, s2, 2
	s_and_b32 s2, s2, 3
	v_writelane_b32 v254, s2, 26
	s_lshl_b32 s2, s3, 9
	v_writelane_b32 v254, s3, 27
	s_ashr_i32 s3, s2, 31
	v_writelane_b32 v254, s2, 28
	s_cmp_lt_i32 s13, 0
	s_nop 0
	v_writelane_b32 v254, s3, 29
	s_movk_i32 s2, 0xe8
	s_cselect_b32 s2, s2, 0xe7
	s_mul_i32 s2, s13, s2
	s_cselect_b32 s3, 0x41, 64
	s_add_i32 s2, s2, s8
	s_mul_hi_i32 s4, s2, 0x92492493
	s_add_i32 s4, s4, s2
	s_lshr_b32 s5, s4, 31
	s_ashr_i32 s4, s4, 6
	s_add_i32 s4, s4, s5
	s_mul_i32 s5, s4, 0x70
	s_sub_i32 s5, s2, s5
	s_mul_i32 s2, s3, s13
	s_add_i32 s2, s2, s8
	s_ashr_i32 s3, s2, 31
	s_lshr_b32 s3, s3, 27
	s_add_i32 s3, s2, s3
	v_writelane_b32 v254, s8, 30
	s_and_b32 s8, s3, 0xffffffe0
	s_lshl_b32 s4, s4, 3
	s_sub_i32 s8, s2, s8
	s_sub_i32 s2, 0x84, s4
	s_min_u32 s9, s2, 8
	v_cvt_f32_ubyte0_e32 v1, s9
	v_cvt_f32_i32_e32 v0, s5
	v_rcp_iflag_f32_e32 v2, v1
	s_ashr_i32 s2, s3, 5
	s_lshl_b32 s10, s2, 3
	s_sub_i32 s2, 0x80, s10
	v_mul_f32_e32 v2, v0, v2
	s_min_i32 s11, s2, 8
	s_ashr_i32 s2, s5, 30
	v_trunc_f32_e32 v2, v2
	s_or_b32 s12, s2, 1
	v_fma_f32 v0, -v2, v1, v0
	v_writelane_b32 v254, s13, 31
	s_lshr_b32 s2, s13, 31
	v_writelane_b32 v254, s2, 32
	v_cmp_ge_f32_e64 s[2:3], |v0|, v1
	v_cvt_i32_f32_e32 v0, v2
	s_and_b64 s[2:3], s[2:3], exec
	s_cselect_b32 s2, s12, 0
	v_cvt_f32_i32_e32 v1, s8
	v_readfirstlane_b32 s3, v0
	s_add_i32 s2, s3, s2
	s_mul_i32 s3, s2, s9
	s_sub_i32 s3, s5, s3
	s_sext_i32_i8 s3, s3
	s_add_i32 s12, s4, s3
	s_sext_i32_i8 s3, s11
	v_cvt_f32_i32_e32 v0, s3
	s_bfe_i64 s[4:5], s[2:3], 0x80000
	s_lshl_b64 s[4:5], s[4:5], 19
	v_writelane_b32 v254, s4, 33
	v_rcp_iflag_f32_e32 v2, v0
	s_ashr_i32 s13, s12, 31
	v_writelane_b32 v254, s5, 34
	s_mov_b32 s4, s12
	v_mul_f32_e32 v2, v1, v2
	v_writelane_b32 v254, s4, 35
	s_xor_b32 s3, s8, s3
	v_trunc_f32_e32 v2, v2
	v_writelane_b32 v254, s5, 36
	s_lshl_b64 s[4:5], s[12:13], 19
	s_ashr_i32 s3, s3, 30
	v_fma_f32 v1, -v2, v0, v1
	v_writelane_b32 v254, s4, 37
	s_or_b32 s3, s3, 1
	s_sext_i32_i8 s2, s2
	v_writelane_b32 v254, s5, 38
	v_cmp_ge_f32_e64 s[4:5], |v1|, |v0|
	s_and_b64 s[4:5], s[4:5], exec
	s_load_dword s5, s[0:1], 0xe8
	v_cvt_i32_f32_e32 v0, v2
	s_mul_i32 s4, s75, s74
	v_mov_b32_e32 v1, 0
	s_movk_i32 s75, 0x84
	s_waitcnt lgkmcnt(0)
	s_mul_i32 s4, s4, s5
	v_writelane_b32 v254, s4, 39
	v_writelane_b32 v254, s2, 40
	s_cselect_b32 s2, s3, 0
	v_readfirstlane_b32 s3, v0
	s_add_i32 s2, s3, s2
	s_mul_i32 s3, s2, s11
	s_sub_i32 s3, s8, s3
	s_sext_i32_i8 s3, s3
	s_add_i32 s10, s10, s3
	s_ashr_i32 s3, s10, 5
	s_mul_i32 s3, s3, 33
	s_and_b32 s4, s10, 31
	s_add_i32 s3, s4, s3
	s_mul_i32 s4, s6, 33
	v_writelane_b32 v254, s4, 41
	s_mul_i32 s4, s7, 33
	v_writelane_b32 v254, s4, 42
	s_sext_i32_i8 s2, s2
	v_writelane_b32 v254, s2, 43
	s_add_i32 s2, s3, 1
	v_writelane_b32 v254, s2, 44
	s_add_i32 s2, 0, 0x23fd0
	v_writelane_b32 v254, s2, 45
	s_add_i32 s2, 0, 0x23fd4
	v_writelane_b32 v254, s2, 46
	s_add_i32 s2, 0, 0x17400
	v_writelane_b32 v254, s2, 47
	s_add_i32 s2, 0, 0x17300
	v_writelane_b32 v254, s2, 48
	s_add_i32 s2, 0, 0x12b00
	v_writelane_b32 v254, s2, 49
	s_add_i32 s2, 0, 0x11000
	v_writelane_b32 v254, s2, 50
	s_mov_b64 s[2:3], 0
	v_writelane_b32 v254, s2, 51
	v_mbcnt_lo_u32_b32 v0, -1, 0
	v_mbcnt_hi_u32_b32 v197, -1, v0
	v_writelane_b32 v254, s3, 52
	v_writelane_b32 v254, s30, 53
	v_writelane_b32 v254, s34, 54
	v_writelane_b32 v254, s35, 55
	v_writelane_b32 v254, s73, 56
	v_writelane_b32 v254, s76, 57
	v_writelane_b32 v254, s77, 58
	v_writelane_b32 v254, s78, 59
	v_writelane_b32 v254, s79, 60
	v_writelane_b32 v254, s78, 61
	v_writelane_b32 v254, s80, 62
	v_writelane_b32 v255, s2, 2
	v_writelane_b32 v255, s3, 3
	v_writelane_b32 v255, s4, 4
	v_writelane_b32 v255, s5, 5
	v_writelane_b32 v255, s6, 6
	v_writelane_b32 v255, s7, 7
	v_writelane_b32 v255, s8, 8
	v_writelane_b32 v255, s9, 9
	v_writelane_b32 v255, s10, 10
	v_writelane_b32 v255, s11, 11
	v_writelane_b32 v255, s12, 12
	v_writelane_b32 v255, s13, 13
	v_writelane_b32 v255, s14, 14
	v_writelane_b32 v255, s15, 15
	v_writelane_b32 v255, s16, 16
	v_writelane_b32 v255, s17, 17
	v_writelane_b32 v255, s18, 18
	v_writelane_b32 v255, s19, 19
	v_writelane_b32 v255, s20, 20
	v_mov_b32_e32 v84, v3
	v_mov_b32_e32 v85, v4
	v_mov_b32_e32 v86, v5
	v_mov_b32_e32 v87, v6
	v_mov_b32_e32 v88, v7
	v_mov_b32_e32 v89, v8
	v_mov_b32_e32 v90, v9
	v_mov_b32_e32 v91, v10
	v_mov_b32_e32 v92, v11
	v_mov_b32_e32 v93, v12
	v_mov_b32_e32 v94, v13
	v_mov_b32_e32 v95, v14
	v_mov_b32_e32 v96, v15
	v_mov_b32_e32 v97, v16
	v_mov_b32_e32 v98, v17
	v_mov_b32_e32 v1, 0
	s_mov_b32 s99, 0xabcd0001
	s_branch .LBB0_152
.Lp0_sync_ret:
	s_mov_b32 s99, 0
	v_readlane_b32 s2, v255, 2
	v_readlane_b32 s3, v255, 3
	v_readlane_b32 s4, v255, 4
	v_readlane_b32 s5, v255, 5
	v_readlane_b32 s6, v255, 6
	v_readlane_b32 s7, v255, 7
	v_readlane_b32 s8, v255, 8
	v_readlane_b32 s9, v255, 9
	v_readlane_b32 s10, v255, 10
	v_readlane_b32 s11, v255, 11
	v_readlane_b32 s12, v255, 12
	v_readlane_b32 s13, v255, 13
	v_readlane_b32 s14, v255, 14
	v_readlane_b32 s15, v255, 15
	v_readlane_b32 s16, v255, 16
	v_readlane_b32 s17, v255, 17
	v_readlane_b32 s18, v255, 18
	v_readlane_b32 s19, v255, 19
	v_readlane_b32 s20, v255, 20
	v_mov_b32_e32 v3, v84
	v_mov_b32_e32 v4, v85
	v_mov_b32_e32 v5, v86
	v_mov_b32_e32 v6, v87
	v_mov_b32_e32 v7, v88
	v_mov_b32_e32 v8, v89
	v_mov_b32_e32 v9, v90
	v_mov_b32_e32 v10, v91
	v_mov_b32_e32 v11, v92
	v_mov_b32_e32 v12, v93
	v_mov_b32_e32 v13, v94
	v_mov_b32_e32 v14, v95
	v_mov_b32_e32 v15, v96
	v_mov_b32_e32 v16, v97
	v_mov_b32_e32 v17, v98
	s_mov_b64 s[4:5], -1
	s_mov_b32 s6, s47
	s_branch .LBB0_81

.LBB0_204:
	s_or_b64 exec, exec, s[2:3]
	v_readlane_b32 s2, v254, 51
	v_readlane_b32 s3, v254, 52
	s_xor_b64 s[2:3], s[2:3], -1
	v_writelane_b32 v252, s2, 12
	v_readlane_b32 s10, v254, 15
	s_mov_b32 s6, 27
	v_writelane_b32 v252, s3, 13
	s_mov_b32 s4, 27
	s_mov_b32 s2, 27
	v_mov_b32_e32 v10, v196
	v_readlane_b32 s11, v254, 16
	s_waitcnt lgkmcnt(0)
	s_barrier
	s_cmp_eq_u32 s99, 0xabcd0001
	s_cbranch_scc1 .Lp0_sync_ret
	s_and_b64 vcc, exec, s[10:11]
	v_readfirstlane_b32 s8, v10
	s_cbranch_vccz .LBB0_220
	s_ashr_i32 s7, s6, 31
	s_lshl_b64 s[6:7], s[6:7], 3
	s_add_u32 s6, s0, s6
	s_addc_u32 s7, s1, s7
	s_load_dwordx2 s[6:7], s[6:7], 0x0
	v_lshlrev_b32_e32 v0, 4, v10
	v_add_u32_e32 v2, 0x2000, v0
	v_ashrrev_i32_e32 v3, 31, v2
	v_lshrrev_b32_e32 v3, 22, v3
	v_add_u32_e32 v3, v2, v3
	s_waitcnt lgkmcnt(0)
	s_add_u32 s24, s6, 0x3a00000
	v_ashrrev_i32_e32 v11, 10, v3
	s_addc_u32 s25, s7, 0
	s_ashr_i32 s5, s4, 31
	v_mul_i32_i24_e32 v3, 0x400, v11
	s_lshl_b64 s[4:5], s[4:5], 3
	v_sub_u32_e32 v2, v2, v3
	s_add_u32 s4, s0, s4
	v_lshrrev_b32_e32 v3, 4, v2
	s_addc_u32 s5, s1, s5
	v_bitop3_b32 v2, v3, v2, 32 bitop3:0x6c
	s_load_dwordx2 s[4:5], s[4:5], 0x0
	v_ashrrev_i32_e32 v3, 31, v2
	v_lshrrev_b32_e32 v3, 26, v3
	v_add_u32_e32 v3, v2, v3
	v_lshlrev_b32_e32 v4, 3, v11
	v_ashrrev_i32_e32 v12, 6, v3
	v_and_b32_e32 v4, -16, v4
	v_add_u32_e32 v4, v12, v4
	s_waitcnt lgkmcnt(0)
	s_add_u32 s26, s4, 0x100000
	v_and_b32_e32 v5, 3, v12
	s_mov_b32 s4, 0x1fffe0
	v_lshrrev_b32_e32 v6, 2, v4
	v_lshlrev_b32_e32 v7, 1, v4
	v_and_b32_e32 v3, 0xc0, v3
	v_and_or_b32 v5, v4, s4, v5
	v_and_b32_e32 v6, 4, v6
	v_and_b32_e32 v7, 24, v7
	v_sub_u32_e32 v2, v2, v3
	v_or3_b32 v5, v5, v6, v7
	v_lshlrev_b32_e32 v6, 5, v11
	v_ashrrev_i16_sdwa v2, v199, sext(v2) dst_sel:DWORD dst_unused:UNUSED_PAD src0_sel:DWORD src1_sel:BYTE_0
	v_and_b32_e32 v6, 32, v6
	v_bfe_i32 v13, v2, 0, 16
	v_add_lshl_u32 v2, v6, v13, 1
	v_lshl_add_u32 v130, v5, 11, v2
	v_lshl_add_u32 v132, v4, 11, v2
	v_bfe_i32 v2, v10, 27, 1
	v_lshrrev_b32_e32 v2, 22, v2
	v_add_u32_e32 v2, v0, v2
	v_and_b32_e32 v2, 0xfffffc00, v2
	v_sub_u32_e32 v0, v0, v2
	v_lshrrev_b32_e32 v2, 4, v0
	v_ashrrev_i32_e32 v3, 31, v10
	v_bitop3_b32 v0, v2, v0, 32 bitop3:0x6c
	v_lshrrev_b32_e32 v3, 26, v3
	v_ashrrev_i32_e32 v2, 31, v0
	v_add_u32_e32 v3, v10, v3
	s_addc_u32 s27, s5, 0
	s_ashr_i32 s3, s2, 31
	v_lshrrev_b32_e32 v2, 26, v2
	v_ashrrev_i32_e32 v15, 6, v3
	s_lshl_b64 s[2:3], s[2:3], 3
	v_add_u32_e32 v2, v0, v2
	v_lshlrev_b32_e32 v3, 3, v15
	s_add_u32 s2, s0, s2
	v_ashrrev_i32_e32 v14, 6, v2
	v_and_b32_e32 v3, -16, v3
	s_addc_u32 s3, s1, s3
	s_ashr_i32 s7, s8, 6
	v_add_u32_e32 v3, v14, v3
	v_and_b32_e32 v4, 3, v14
	s_ashr_i32 s6, s8, 8
	s_lshl_b32 s28, s7, 10
	v_and_or_b32 v4, v3, s4, v4
	v_lshrrev_b32_e32 v5, 2, v3
	v_lshlrev_b32_e32 v6, 1, v3
	v_and_b32_e32 v2, 0xc0, v2
	v_readlane_b32 s4, v254, 37
	v_and_b32_e32 v5, 4, v5
	v_and_b32_e32 v6, 24, v6
	v_sub_u32_e32 v0, v0, v2
	v_readlane_b32 s5, v254, 38
	s_add_u32 s18, s24, s4
	v_or3_b32 v4, v4, v5, v6
	v_lshlrev_b32_e32 v5, 5, v15
	v_ashrrev_i16_sdwa v0, v199, sext(v0) dst_sel:DWORD dst_unused:UNUSED_PAD src0_sel:DWORD src1_sel:BYTE_0
	s_addc_u32 s19, s25, s5
	v_readlane_b32 s4, v254, 33
	v_and_b32_e32 v5, 32, v5
	v_bfe_i32 v16, v0, 0, 16
	v_readlane_b32 s5, v254, 34
	s_add_u32 s20, s26, s4
	v_add_lshl_u32 v2, v5, v16, 1
	s_addc_u32 s21, s27, s5
	s_add_i32 s29, s28, 0
	v_lshl_add_u32 v0, v4, 11, v2
	s_add_i32 m0, s29, 0x10000
	v_lshl_add_u32 v134, v3, 11, v2
	global_load_lds_dwordx4 v0, s[20:21]
	s_add_i32 m0, s29, 0x12000
	s_add_u32 s4, s20, 0x40000
	global_load_lds_dwordx4 v130, s[20:21]
	s_addc_u32 s5, s21, 0
	s_add_i32 m0, s29, 0x14000
	s_add_i32 s30, s29, 0x2000
	global_load_lds_dwordx4 v0, s[4:5]
	s_add_i32 m0, s29, 0x16000
	v_mov_b32_e32 v131, v1
	global_load_lds_dwordx4 v130, s[4:5]
	s_mov_b32 m0, s29
	s_add_u32 s4, s18, 0x40000
	global_load_lds_dwordx4 v134, s[18:19]
	s_mov_b32 m0, s30
	s_addc_u32 s5, s19, 0
	s_add_i32 s31, s29, 0x4000
	global_load_lds_dwordx4 v132, s[18:19]
	s_mov_b32 m0, s31
	s_add_i32 s34, s29, 0x6000
	global_load_lds_dwordx4 v134, s[4:5]
	s_mov_b32 m0, s34
	v_mov_b32_e32 v135, v1
	global_load_lds_dwordx4 v132, s[4:5]
	s_load_dwordx2 s[4:5], s[2:3], 0x0
	v_mov_b32_e32 v133, v1
	s_cmp_eq_u32 s6, 1
	v_lshl_add_u64 v[8:9], s[20:21], 0, v[0:1]
	v_lshl_add_u64 v[6:7], s[20:21], 0, v[130:131]
	v_lshl_add_u64 v[2:3], s[18:19], 0, v[134:135]
	s_cselect_b64 s[2:3], -1, 0
	s_cmp_lg_u32 s6, 1
	v_lshl_add_u64 v[4:5], s[18:19], 0, v[132:133]
	s_cbranch_scc1 .LBB0_207
	s_barrier

	.amdhsa_kernel _Z14fwd_megakernel5KArgs
		.amdhsa_group_segment_fixed_size 0
		.amdhsa_private_segment_fixed_size 0
		.amdhsa_kernarg_size 480
		.amdhsa_user_sgpr_count 2
		.amdhsa_user_sgpr_dispatch_ptr 0
		.amdhsa_user_sgpr_queue_ptr 0
		.amdhsa_user_sgpr_kernarg_segment_ptr 1
		.amdhsa_user_sgpr_dispatch_id 0
		.amdhsa_user_sgpr_kernarg_preload_length 0
		.amdhsa_user_sgpr_kernarg_preload_offset 0
		.amdhsa_user_sgpr_private_segment_size 0
		.amdhsa_uses_dynamic_stack 0
		.amdhsa_enable_private_segment 0
		.amdhsa_system_sgpr_workgroup_id_x 1
		.amdhsa_system_sgpr_workgroup_id_y 0
		.amdhsa_system_sgpr_workgroup_id_z 0
		.amdhsa_system_sgpr_workgroup_info 0
		.amdhsa_system_vgpr_workitem_id 2
		.amdhsa_next_free_vgpr 256
		.amdhsa_next_free_sgpr 102
		.amdhsa_accum_offset 256
		.amdhsa_reserve_vcc 1
		.amdhsa_float_round_mode_32 0
		.amdhsa_float_round_mode_16_64 0
		.amdhsa_float_denorm_mode_32 3
		.amdhsa_float_denorm_mode_16_64 3
		.amdhsa_dx10_clamp 1
		.amdhsa_ieee_mode 1
		.amdhsa_fp16_overflow 0
		.amdhsa_tg_split 0
		.amdhsa_exception_fp_ieee_invalid_op 0
		.amdhsa_exception_fp_denorm_src 0
		.amdhsa_exception_fp_ieee_div_zero 0
		.amdhsa_exception_fp_ieee_overflow 0
		.amdhsa_exception_fp_ieee_underflow 0
		.amdhsa_exception_fp_ieee_inexact 0
		.amdhsa_exception_int_div_zero 0
	.end_amdhsa_kernel

amdhsa.kernels:
  - .agpr_count:     0
    .args:
      - .offset:         0
        .size:           224
        .value_kind:     by_value
      - .offset:         224
        .size:           4
        .value_kind:     hidden_block_count_x
      - .offset:         228
        .size:           4
        .value_kind:     hidden_block_count_y
      - .offset:         232
        .size:           4
        .value_kind:     hidden_block_count_z
      - .offset:         236
        .size:           2
        .value_kind:     hidden_group_size_x
      - .offset:         238
        .size:           2
        .value_kind:     hidden_group_size_y
      - .offset:         240
        .size:           2
        .value_kind:     hidden_group_size_z
      - .offset:         242
        .size:           2
        .value_kind:     hidden_remainder_x
      - .offset:         244
        .size:           2
        .value_kind:     hidden_remainder_y
      - .offset:         246
        .size:           2
        .value_kind:     hidden_remainder_z
      - .offset:         264
        .size:           8
        .value_kind:     hidden_global_offset_x
      - .offset:         272
        .size:           8
        .value_kind:     hidden_global_offset_y
      - .offset:         280
        .size:           8
        .value_kind:     hidden_global_offset_z
      - .offset:         288
        .size:           2
        .value_kind:     hidden_grid_dims
      - .offset:         312
        .size:           8
        .value_kind:     hidden_multigrid_sync_arg
      - .offset:         344
        .size:           4
        .value_kind:     hidden_dynamic_lds_size
    .group_segment_fixed_size: 0
    .kernarg_segment_align: 8
    .kernarg_segment_size: 480
    .language:       OpenCL C
    .language_version:
      - 2
      - 0
    .max_flat_workgroup_size: 512
    .name:           _Z14fwd_megakernel5KArgs
    .private_segment_fixed_size: 0
    .sgpr_count:     108
    .sgpr_spill_count: 196
    .symbol:         _Z14fwd_megakernel5KArgs.kd
    .uniform_work_group_size: 1
    .uses_dynamic_stack: false
    .vgpr_count:     256
    .vgpr_spill_count: 0
    .wavefront_size: 64
